# attA: two 64-key tiles per workgroup barrier (ring as pair double buffer), permlane32_swap row-max exchange
# speedup vs baseline: 1.2469x; 1.0049x over previous
; __device__ __forceinline__ void unit(LAS unsigned char* lds, bf16_t* P1, const bf16_t* vaT, int b, int h, int qblk, float lam, const float* subln_w, const float* khalf) {
;     ...
;     for (int jj = 0; jj < NT; ++jj) {
;         const int j = NT - 1 - jj;
;         { const bool done = __all(qbound + sl2 * (float)(64 * j + 63 - qrow) < m - 24.f);
;           if (lane == 0) dflag[(jj & 1) * 8 + wid] = done ? 1 : 0; }
;         if (jj + 2 < NT) asm volatile("s_waitcnt vmcnt(8) lgkmcnt(0)\n\ts_barrier" ::: "memory"); else if (jj + 1 < NT) asm volatile("s_waitcnt vmcnt(4) lgkmcnt(0)\n\ts_barrier" ::: "memory"); else asm volatile("s_waitcnt vmcnt(0) lgkmcnt(0)\n\ts_barrier" ::: "memory");
.La_top:
	v_add_u32_e32 v0, s76, v190
	v_add_u32_e32 v66, 0x7f, v0
	v_cvt_f32_i32_e32 v66, v66
	s_mov_b64 s[2:3], exec
	v_mul_f32_e32 v120, v127, v66
	v_pk_add_f32 v[142:143], v[132:133], v[120:121]
	s_nop 0
	v_cmp_lt_f32_e32 vcc, v142, v143
	s_and_saveexec_b64 s[4:5], s[0:1]
	s_cbranch_execz .La_flag_done
	s_cmp_eq_u64 vcc, s[2:3]
	s_cselect_b64 s[2:3], -1, 0
	v_cndmask_b32_e64 v66, 0, 1, s[2:3]
	s_and_b32 s2, s81, 2
	s_lshl_b32 s2, s2, 4
	s_add_i32 s2, s74, s2
	v_mov_b32_e32 v67, s2
	ds_write_b32 v67, v66
.La_flag_done:
	s_or_b64 exec, exec, s[4:5]
	s_cmp_lg_u32 s81, 0
	s_cbranch_scc1 .La_w0
	s_cmp_gt_u32 s73, 2
	s_cbranch_scc0 .La_w0
	s_waitcnt vmcnt(4) lgkmcnt(0)
	s_barrier
	s_branch .La_after_bar

; #define LAS __attribute__((address_space(3)))
; #define MFMA32(a, b, c) __builtin_amdgcn_mfma_f32_32x32x16_bf16((a), (b), (c), 0, 0, 0)
; __device__ __forceinline__ void unit(LAS unsigned char* lds, bf16_t* P1, const bf16_t* vaT, int b, int h, int qblk, float lam, const float* subln_w, const float* khalf) {
;     ...
;         { typedef int i32x4 __attribute__((ext_vector_type(4)));
;           const i32x4 fa = *(const LAS i32x4*)(lds + 4 * STG + (jj & 1) * 32), fb = *(const LAS i32x4*)(lds + 4 * STG + (jj & 1) * 32 + 16);
;           if (((fa[0] + fa[1]) + (fa[2] + fa[3])) + ((fb[0] + fb[1]) + (fb[2] + fb[3])) == 8) break; }
;         if (jj + 3 < NT) { DMA_TILE(j - 3, (stg + 3) & 3); }
;         const LAS unsigned char* kb = lds + stg * STG;
;         stg = (stg + 1) & 3;
;         f32x16 S0, S1;
;         { float slv = sl2; asm volatile("" : "+v"(slv));
; #pragma unroll
;           for (int r = 0; r < 16; ++r) { S0[r] = __builtin_fmaf(slv, (float)((r & 3) + 8 * (r >> 2)), sl2h); S1[r] = S0[r]; } }
; #pragma unroll
;         for (int ks = 0; ks < 4; ++ks) {
;             const bf16x8 a0 = *(const LAS bf16x8*)(kb + koff[ks]);
;             const bf16x8 a1 = *(const LAS bf16x8*)(kb + koff[ks] + 32 * 256);
;             S0 = MFMA32(a0, qf[ks], S0); S1 = MFMA32(a1, qf[ks], S1);
;         }
.La_after_bar:
	s_and_b32 s2, s81, 2
	s_lshl_b32 s2, s2, 4
	s_add_i32 s2, s2, 0x20000
	v_mov_b32_e32 v70, s2
	s_lshl_b32 s82, s80, 15
	s_add_i32 s83, s82, 0x8000
	s_sub_i32 s100, s76, 64
	ds_read_b128 v[66:69], v70
	ds_read_b128 v[70:73], v70 offset:16
	v_add3_u32 v120, s82, v129, v151
	v_add3_u32 v201, s82, v185, v151
	ds_read_b128 v[192:195], v120
	ds_read_b128 v[196:199], v120 offset:8192
	v_add3_u32 v120, s82, v186, v151
	ds_read_b128 v[202:205], v201
	ds_read_b128 v[206:209], v201 offset:8192
	v_add3_u32 v201, s82, v187, v151
	ds_read_b128 v[210:213], v120
	ds_read_b128 v[214:217], v120 offset:8192
	ds_read_b128 v[218:221], v201
	ds_read_b128 v[222:225], v201 offset:8192
	s_waitcnt lgkmcnt(8)
	v_add3_u32 v66, v66, v67, v68
	v_add3_u32 v69, v69, v70, v71
	v_add_u32_e32 v72, v72, v73
	v_add3_u32 v66, v66, v69, v72
	v_cmp_eq_u32_e32 vcc, 8, v66
	s_cbranch_vccnz .LBB0_420
	s_cmp_lt_u32 s81, 2
	s_cbranch_scc1 .La_qk_nodmaA
	s_add_i32 s5, s81, 2
	s_cmp_ge_u32 s5, s73
	s_cbranch_scc1 .La_qk_nodmaA
	s_add_i32 s5, s82, 0x10000
	s_and_b32 s5, s5, 0x18000
	s_add_i32 s5, s72, s5
	s_mov_b32 m0, s5
	s_waitcnt lgkmcnt(4)
	v_mfma_f32_32x32x16_bf16 v[82:97], v[192:195], v[98:101], v[226:241]
	global_load_lds_dwordx4 v[140:141], off
	s_add_i32 m0, s5, 0x400
	v_mfma_f32_32x32x16_bf16 v[66:81], v[196:199], v[98:101], v[226:241]
	global_load_lds_dwordx4 v[138:139], off
	s_add_i32 m0, s5, 0x4000
	v_mfma_f32_32x32x16_bf16 v[82:97], v[202:205], v[102:105], v[82:97]
	global_load_lds_dwordx4 v134, s[44:45]
	s_add_i32 m0, s5, 0x4400
	v_mfma_f32_32x32x16_bf16 v[66:81], v[206:209], v[102:105], v[66:81]
	global_load_lds_dwordx4 v136, s[44:45]
	s_waitcnt lgkmcnt(0)
	v_mfma_f32_32x32x16_bf16 v[82:97], v[210:213], v[106:109], v[82:97]
	v_mfma_f32_32x32x16_bf16 v[66:81], v[214:217], v[106:109], v[66:81]
	v_mfma_f32_32x32x16_bf16 v[82:97], v[218:221], v[110:113], v[82:97]
	v_mfma_f32_32x32x16_bf16 v[66:81], v[222:225], v[110:113], v[66:81]
	s_add_u32 s44, s44, 0xffffff80
	s_addc_u32 s45, s45, -1
	v_lshl_add_u64 v[138:139], v[138:139], 0, s[38:39]
	v_lshl_add_u64 v[140:141], v[140:141], 0, s[38:39]
	s_branch .La_qk_doneA

; __device__ __forceinline__ int crow(int r, int hi) { return (r & 3) + 8 * (r >> 2) + 4 * hi; }
; __device__ __forceinline__ float ex2(float v) { return __builtin_amdgcn_exp2f(v); }
; __device__ __forceinline__ void unit(LAS unsigned char* lds, bf16_t* P1, const bf16_t* vaT, int b, int h, int qblk, float lam, const float* subln_w, const float* khalf) {
;     ...
;         const int kv0 = 64 * j;
;         if (j >= NT - 2) {
; #pragma unroll
;             for (int r = 0; r < 16; ++r) { const int kv = kv0 + crow(r, hi); if (kv > qrow) S0[r] = -INFINITY; if (kv + 32 > qrow) S1[r] = -INFINITY; }
;         }
;         const float tb0 = sl2 * (float)(kv0 - qrow), tb1 = tb0 + sl2 * 32.f;
;         float mx0 = S0[0], mx1 = S1[0];
; #pragma unroll
;         for (int r = 1; r < 16; ++r) { mx0 = fmaxf(mx0, S0[r]); mx1 = fmaxf(mx1, S1[r]); }
;         float mt = fmaxf(mx0 + tb0, mx1 + tb1); mt = fmaxf(mt, __shfl_xor(mt, 32));
;         const bool skip = __all((mt < m - 24.f) || (mt == -INFINITY));
;         if (!skip) {
;         const float mn = fmaxf(m, mt); const float alpha = ex2(m - mn); m = mn;
;         const float c0 = tb0 - mn, c1 = tb1 - mn;
;         f32x2 ps2 = (f32x2){0.f, 0.f};
.La_qk_doneA:
	v_add_u32_e32 v244, s82, v168
	v_add_u32_e32 v245, s82, v169
	v_add_u32_e32 v246, s82, v170
	v_add_u32_e32 v247, s82, v171
	ds_read_b128 v[192:195], v244 offset:16384
	ds_read_b128 v[196:199], v244 offset:20480
	ds_read_b128 v[202:205], v244 offset:24576
	ds_read_b128 v[206:209], v244 offset:28672
	ds_read_b128 v[210:213], v245 offset:16384
	ds_read_b128 v[214:217], v245 offset:20480
	ds_read_b128 v[218:221], v245 offset:24576
	ds_read_b128 v[222:225], v245 offset:28672
	s_cmp_lg_u32 s81, 0
	s_cbranch_scc1 .La_nomaskA
	v_add_u32_e32 v243, s76, v189
	v_add_u32_e32 v250, 0x60, v243
	v_add_u32_e32 v251, 64, v243
	v_cmp_le_i32_e32 vcc, v250, v125
	s_nop 6
	v_cndmask_b32_e32 v66, v184, v66, vcc
	v_cmp_lt_i32_e32 vcc, v251, v125
	s_nop 1
	v_cndmask_b32_e32 v83, v184, v83, vcc
	v_cmp_le_i32_e32 vcc, v251, v125
	v_add_u32_e32 v251, 0x61, v243
	s_nop 0
	v_cndmask_b32_e32 v82, v184, v82, vcc
	v_cmp_le_i32_e32 vcc, v251, v125
	v_add_u32_e32 v251, 0x42, v243
	s_nop 0
	v_cndmask_b32_e32 v67, v184, v67, vcc
	v_cmp_le_i32_e32 vcc, v251, v125
	v_add_u32_e32 v251, 0x62, v243
	s_nop 0
	v_cndmask_b32_e32 v84, v184, v84, vcc
	v_cmp_le_i32_e32 vcc, v251, v125
	v_add_u32_e32 v251, 0x43, v243
	s_nop 0
	v_cndmask_b32_e32 v68, v184, v68, vcc
	v_cmp_le_i32_e32 vcc, v251, v125
	v_add_u32_e32 v251, 0x63, v243
	s_nop 0
	v_cndmask_b32_e32 v85, v184, v85, vcc
	v_cmp_le_i32_e32 vcc, v251, v125
	v_add_u32_e32 v251, 0x48, v243
	s_nop 0
	v_cndmask_b32_e32 v69, v184, v69, vcc
	v_cmp_le_i32_e32 vcc, v251, v125
	v_add_u32_e32 v251, 0x68, v243
	s_nop 0
	v_cndmask_b32_e32 v86, v184, v86, vcc
	v_cmp_le_i32_e32 vcc, v251, v125
	v_add_u32_e32 v251, 0x49, v243
	s_nop 0
	v_cndmask_b32_e32 v70, v184, v70, vcc
	v_cmp_le_i32_e32 vcc, v251, v125
	v_add_u32_e32 v251, 0x69, v243
	s_nop 0
	v_cndmask_b32_e32 v87, v184, v87, vcc
	v_cmp_le_i32_e32 vcc, v251, v125
	v_add_u32_e32 v251, 0x4a, v243
	s_nop 0
	v_cndmask_b32_e32 v71, v184, v71, vcc
	v_cmp_le_i32_e32 vcc, v251, v125
	v_add_u32_e32 v251, 0x6a, v243
	s_nop 0
	v_cndmask_b32_e32 v88, v184, v88, vcc
	v_cmp_le_i32_e32 vcc, v251, v125
	v_add_u32_e32 v251, 0x4b, v243
	s_nop 0
	v_cndmask_b32_e32 v72, v184, v72, vcc
	v_cmp_le_i32_e32 vcc, v251, v125
	v_add_u32_e32 v251, 0x6b, v243
	s_nop 0
	v_cndmask_b32_e32 v89, v184, v89, vcc
	v_cmp_le_i32_e32 vcc, v251, v125
	v_add_u32_e32 v251, 0x50, v243
	s_nop 0
	v_cndmask_b32_e32 v73, v184, v73, vcc
	v_cmp_le_i32_e32 vcc, v251, v125
	v_add_u32_e32 v251, 0x70, v243
	s_nop 0
	v_cndmask_b32_e32 v90, v184, v90, vcc
	v_cmp_le_i32_e32 vcc, v251, v125
	v_add_u32_e32 v251, 0x51, v243
	s_nop 0
	v_cndmask_b32_e32 v74, v184, v74, vcc
	v_cmp_le_i32_e32 vcc, v251, v125
	v_add_u32_e32 v251, 0x71, v243
	s_nop 0
	v_cndmask_b32_e32 v91, v184, v91, vcc
	v_cmp_le_i32_e32 vcc, v251, v125
	v_add_u32_e32 v251, 0x52, v243
	s_nop 0
	v_cndmask_b32_e32 v75, v184, v75, vcc
	v_cmp_le_i32_e32 vcc, v251, v125
	v_add_u32_e32 v251, 0x72, v243
	s_nop 0
	v_cndmask_b32_e32 v92, v184, v92, vcc
	v_cmp_le_i32_e32 vcc, v251, v125
	v_add_u32_e32 v251, 0x53, v243
	s_nop 0
	v_cndmask_b32_e32 v76, v184, v76, vcc
	v_cmp_le_i32_e32 vcc, v251, v125
	v_add_u32_e32 v251, 0x73, v243
	s_nop 0
	v_cndmask_b32_e32 v93, v184, v93, vcc
	v_cmp_le_i32_e32 vcc, v251, v125
	v_add_u32_e32 v251, 0x58, v243
	s_nop 0
	v_cndmask_b32_e32 v77, v184, v77, vcc
	v_cmp_le_i32_e32 vcc, v251, v125
	v_add_u32_e32 v251, 0x78, v243
	s_nop 0
	v_cndmask_b32_e32 v94, v184, v94, vcc
	v_cmp_le_i32_e32 vcc, v251, v125
	v_add_u32_e32 v251, 0x59, v243
	s_nop 0
	v_cndmask_b32_e32 v78, v184, v78, vcc
	v_cmp_le_i32_e32 vcc, v251, v125
	v_add_u32_e32 v251, 0x79, v243
	s_nop 0
	v_cndmask_b32_e32 v95, v184, v95, vcc
	v_cmp_le_i32_e32 vcc, v251, v125
	v_add_u32_e32 v251, 0x5a, v243
	s_nop 0
	v_cndmask_b32_e32 v79, v184, v79, vcc
	v_cmp_le_i32_e32 vcc, v251, v125
	v_add_u32_e32 v251, 0x7a, v243
	s_nop 0
	v_cndmask_b32_e32 v96, v184, v96, vcc
	v_cmp_le_i32_e32 vcc, v251, v125
	v_add_u32_e32 v251, 0x5b, v243
	v_add_u32_e32 v243, 0x7b, v243
	v_cndmask_b32_e32 v80, v184, v80, vcc
	v_cmp_le_i32_e32 vcc, v251, v125
	s_nop 1
	v_cndmask_b32_e32 v97, v184, v97, vcc
	v_cmp_le_i32_e32 vcc, v243, v125
	s_nop 1
	v_cndmask_b32_e32 v81, v184, v81, vcc
.La_nomaskA:
	v_add_u32_e32 v0, s76, v190
	v_add_u32_e32 v0, 64, v0
	v_cvt_f32_i32_e32 v142, v0
	v_add_f32_e32 v143, v133, v121
	v_max3_f32 v0, v82, v83, v84
	v_max3_f32 v120, v66, v67, v68
	v_max3_f32 v0, v0, v85, v86
	v_max3_f32 v120, v120, v69, v70
	v_max3_f32 v0, v0, v87, v88
	v_max3_f32 v120, v120, v71, v72
	v_max3_f32 v0, v0, v89, v90
	v_max3_f32 v120, v120, v73, v74
	v_max3_f32 v0, v0, v91, v92
	v_max3_f32 v120, v120, v75, v76
	v_max3_f32 v0, v0, v93, v94
	v_max3_f32 v120, v120, v77, v78
	v_max3_f32 v0, v0, v95, v96
	v_max3_f32 v120, v120, v79, v80
	v_max_f32_e32 v0, v0, v97
	v_max_f32_e32 v120, v120, v81
	v_fma_f32 v248, v127, v142, v188
	v_fmac_f32_e32 v0, v127, v142
	v_add_f32_e32 v120, v248, v120
	v_max_f32_e32 v0, v0, v120
	v_mov_b32_e32 v120, v0
	s_nop 1
	v_permlane32_swap_b32_e32 v0, v120
	v_max_f32_e32 v0, v0, v120
	v_cmp_lt_f32_e32 vcc, v0, v143
	v_cmp_eq_f32_e64 s[4:5], v0, v184
	s_or_b64 s[4:5], vcc, s[4:5]
	s_cmp_eq_u64 s[4:5], exec
	s_cbranch_scc1 .La_endA
	v_max_f32_e32 v120, v133, v0
	v_mul_f32_e32 v142, v127, v142
	v_sub_f32_e32 v0, v133, v120
	v_exp_f32_e32 v0, v0
	v_sub_f32_e32 v142, v142, v120
	v_sub_f32_e32 v248, v248, v120
	v_mov_b32_e32 v133, v120
	v_cmp_neq_f32_e32 vcc, 1.0, v0
	s_cbranch_vccz .La_norescaleA
; __device__ __forceinline__ void unit(LAS unsigned char* lds, bf16_t* P1, const bf16_t* vaT, int b, int h, int qblk, float lam, const float* subln_w, const float* khalf) {
;     ...
;         if (__any(alpha != 1.f)) {
; #pragma unroll
;             for (int d = 0; d < 4; ++d) O[d] = O[d] * alpha;
;         }
	v_pk_mul_f32 v[64:65], v[64:65], v[0:1] op_sel_hi:[1,0]
	v_pk_mul_f32 v[62:63], v[62:63], v[0:1] op_sel_hi:[1,0]
	v_pk_mul_f32 v[60:61], v[60:61], v[0:1] op_sel_hi:[1,0]
	v_pk_mul_f32 v[58:59], v[58:59], v[0:1] op_sel_hi:[1,0]
	v_pk_mul_f32 v[56:57], v[56:57], v[0:1] op_sel_hi:[1,0]
	v_pk_mul_f32 v[54:55], v[54:55], v[0:1] op_sel_hi:[1,0]
	v_pk_mul_f32 v[52:53], v[52:53], v[0:1] op_sel_hi:[1,0]
	v_pk_mul_f32 v[50:51], v[50:51], v[0:1] op_sel_hi:[1,0]
	v_pk_mul_f32 v[48:49], v[48:49], v[0:1] op_sel_hi:[1,0]
	v_pk_mul_f32 v[46:47], v[46:47], v[0:1] op_sel_hi:[1,0]
	v_pk_mul_f32 v[44:45], v[44:45], v[0:1] op_sel_hi:[1,0]
	v_pk_mul_f32 v[42:43], v[42:43], v[0:1] op_sel_hi:[1,0]
	v_pk_mul_f32 v[40:41], v[40:41], v[0:1] op_sel_hi:[1,0]
	v_pk_mul_f32 v[38:39], v[38:39], v[0:1] op_sel_hi:[1,0]
	v_pk_mul_f32 v[36:37], v[36:37], v[0:1] op_sel_hi:[1,0]
	v_pk_mul_f32 v[34:35], v[34:35], v[0:1] op_sel_hi:[1,0]
	v_pk_mul_f32 v[32:33], v[32:33], v[0:1] op_sel_hi:[1,0]
	v_pk_mul_f32 v[30:31], v[30:31], v[0:1] op_sel_hi:[1,0]
	v_pk_mul_f32 v[28:29], v[28:29], v[0:1] op_sel_hi:[1,0]
	v_pk_mul_f32 v[26:27], v[26:27], v[0:1] op_sel_hi:[1,0]
	v_pk_mul_f32 v[24:25], v[24:25], v[0:1] op_sel_hi:[1,0]
	v_pk_mul_f32 v[22:23], v[22:23], v[0:1] op_sel_hi:[1,0]
	v_pk_mul_f32 v[20:21], v[20:21], v[0:1] op_sel_hi:[1,0]
	v_pk_mul_f32 v[18:19], v[18:19], v[0:1] op_sel_hi:[1,0]
	v_pk_mul_f32 v[16:17], v[16:17], v[0:1] op_sel_hi:[1,0]
	v_pk_mul_f32 v[14:15], v[14:15], v[0:1] op_sel_hi:[1,0]
	v_pk_mul_f32 v[12:13], v[12:13], v[0:1] op_sel_hi:[1,0]
	v_pk_mul_f32 v[10:11], v[10:11], v[0:1] op_sel_hi:[1,0]
	v_pk_mul_f32 v[8:9], v[8:9], v[0:1] op_sel_hi:[1,0]
	v_pk_mul_f32 v[6:7], v[6:7], v[0:1] op_sel_hi:[1,0]
	v_pk_mul_f32 v[4:5], v[4:5], v[0:1] op_sel_hi:[1,0]
	v_pk_mul_f32 v[2:3], v[2:3], v[0:1] op_sel_hi:[1,0]
; #define LAS __attribute__((address_space(3)))
; __device__ __forceinline__ unsigned cvtpk(float lo, float hi) { return pg8::cvt_pk_bf16(lo, hi); }
; __device__ __forceinline__ void unit(LAS unsigned char* lds, bf16_t* P1, const bf16_t* vaT, int b, int h, int qblk, float lam, const float* subln_w, const float* khalf) {
;     ...
;         if (jj + 3 < NT) { DMA_TILE(j - 3, (stg + 3) & 3); }
;         const LAS unsigned char* kb = lds + stg * STG;
;         stg = (stg + 1) & 3;
;         f32x16 S0, S1;
;         { float slv = sl2; asm volatile("" : "+v"(slv));
; #pragma unroll
;           for (int r = 0; r < 16; ++r) { S0[r] = __builtin_fmaf(slv, (float)((r & 3) + 8 * (r >> 2)), sl2h); S1[r] = S0[r]; } }
; #pragma unroll
;         for (int ks = 0; ks < 4; ++ks) {
;             const bf16x8 a0 = *(const LAS bf16x8*)(kb + koff[ks]);
;             const bf16x8 a1 = *(const LAS bf16x8*)(kb + koff[ks] + 32 * 256);
;             S0 = MFMA32(a0, qf[ks], S0); S1 = MFMA32(a1, qf[ks], S1);
;         }
;     ...
;         f32x2 ps2 = (f32x2){0.f, 0.f};
; #pragma unroll
;         for (int r = 0; r < 16; r += 2) { f32x2 a = (f32x2){S0[r], S0[r + 1]} + c0, bq = (f32x2){S1[r], S1[r + 1]} + c1;
;             a.x = ex2(a.x); a.y = ex2(a.y); bq.x = ex2(bq.x); bq.y = ex2(bq.y); S0[r] = a.x; S0[r + 1] = a.y; S1[r] = bq.x; S1[r + 1] = bq.y; ps2 = ps2 + a; ps2 = ps2 + bq; }
;         l = l * alpha + (ps2.x + ps2.y);
;         if (__any(alpha != 1.f)) {
; #pragma unroll
;             for (int d = 0; d < 4; ++d) O[d] = O[d] * alpha;
;         }
;         u32x4 pk[2][2];
; #pragma unroll
;         for (int s = 0; s < 2; ++s) {
;             pk[0][s] = (u32x4){cvtpk(S0[8 * s + 0], S0[8 * s + 1]), cvtpk(S0[8 * s + 2], S0[8 * s + 3]), cvtpk(S0[8 * s + 4], S0[8 * s + 5]), cvtpk(S0[8 * s + 6], S0[8 * s + 7])};
;             pk[1][s] = (u32x4){cvtpk(S1[8 * s + 0], S1[8 * s + 1]), cvtpk(S1[8 * s + 2], S1[8 * s + 3]), cvtpk(S1[8 * s + 4], S1[8 * s + 5]), cvtpk(S1[8 * s + 6], S1[8 * s + 7])};
;         }
; #pragma unroll
;         for (int d = 0; d < 4; ++d)
; #pragma unroll
;             for (int t2 = 0; t2 < 2; ++t2)
; #pragma unroll
;                 for (int s = 0; s < 2; ++s) {
;                     const bf16x8 vf = *(const LAS bf16x8*)(kb + voff[2 * t2 + s] + d * 32 * 128);
;                     O[d] = MFMA32(vf, __builtin_bit_cast(bf16x8, pk[t2][s]), O[d]);
;                 }
.La_norescaleA:
	v_pk_add_f32 v[82:83], v[82:83], v[142:143] op_sel_hi:[1,0]
	v_pk_add_f32 v[84:85], v[84:85], v[142:143] op_sel_hi:[1,0]
	v_pk_add_f32 v[86:87], v[86:87], v[142:143] op_sel_hi:[1,0]
	v_pk_add_f32 v[88:89], v[88:89], v[142:143] op_sel_hi:[1,0]
	v_exp_f32_e32 v82, v82
	v_exp_f32_e32 v83, v83
	v_exp_f32_e32 v84, v84
	v_exp_f32_e32 v85, v85
	v_exp_f32_e32 v86, v86
	v_exp_f32_e32 v87, v87
	v_exp_f32_e32 v88, v88
	v_exp_f32_e32 v89, v89
	v_pk_add_f32 v[252:253], v[82:83], v[84:85]
	v_cvt_pk_bf16_f32 v82, v82, v83
	v_cvt_pk_bf16_f32 v83, v84, v85
	v_cvt_pk_bf16_f32 v84, v86, v87
	v_cvt_pk_bf16_f32 v85, v88, v89
	v_pk_add_f32 v[252:253], v[252:253], v[86:87]
	v_pk_add_f32 v[252:253], v[252:253], v[88:89]
	s_waitcnt lgkmcnt(0)
	v_mfma_f32_32x32x16_bf16 v[50:65], v[192:195], v[82:85], v[50:65]
	ds_read_b128 v[192:195], v246 offset:16384
	v_pk_add_f32 v[90:91], v[90:91], v[142:143] op_sel_hi:[1,0]
	v_pk_add_f32 v[92:93], v[92:93], v[142:143] op_sel_hi:[1,0]
	v_pk_add_f32 v[94:95], v[94:95], v[142:143] op_sel_hi:[1,0]
	v_pk_add_f32 v[96:97], v[96:97], v[142:143] op_sel_hi:[1,0]
	v_exp_f32_e32 v90, v90
	v_mfma_f32_32x32x16_bf16 v[34:49], v[196:199], v[82:85], v[34:49]
	ds_read_b128 v[196:199], v246 offset:20480
	v_exp_f32_e32 v91, v91
	v_exp_f32_e32 v92, v92
	v_exp_f32_e32 v93, v93
	v_exp_f32_e32 v94, v94
	v_exp_f32_e32 v95, v95
	v_mfma_f32_32x32x16_bf16 v[18:33], v[202:205], v[82:85], v[18:33]
	ds_read_b128 v[202:205], v246 offset:24576
	v_exp_f32_e32 v96, v96
	v_exp_f32_e32 v97, v97
	v_pk_add_f32 v[252:253], v[252:253], v[90:91]
	v_pk_add_f32 v[252:253], v[252:253], v[92:93]
	v_cvt_pk_bf16_f32 v90, v90, v91
	v_mfma_f32_32x32x16_bf16 v[2:17], v[206:209], v[82:85], v[2:17]
	ds_read_b128 v[206:209], v246 offset:28672
	v_cvt_pk_bf16_f32 v91, v92, v93
	v_cvt_pk_bf16_f32 v92, v94, v95
	v_cvt_pk_bf16_f32 v93, v96, v97
	v_pk_add_f32 v[252:253], v[252:253], v[94:95]
	v_pk_add_f32 v[252:253], v[252:253], v[96:97]
	v_mfma_f32_32x32x16_bf16 v[50:65], v[210:213], v[90:93], v[50:65]
	ds_read_b128 v[210:213], v247 offset:16384
	v_pk_add_f32 v[66:67], v[66:67], v[248:249] op_sel_hi:[1,0]
	v_pk_add_f32 v[68:69], v[68:69], v[248:249] op_sel_hi:[1,0]
	v_pk_add_f32 v[70:71], v[70:71], v[248:249] op_sel_hi:[1,0]
	v_pk_add_f32 v[72:73], v[72:73], v[248:249] op_sel_hi:[1,0]
	v_exp_f32_e32 v66, v66
	v_mfma_f32_32x32x16_bf16 v[34:49], v[214:217], v[90:93], v[34:49]
	ds_read_b128 v[214:217], v247 offset:20480
	v_exp_f32_e32 v67, v67
	v_exp_f32_e32 v68, v68
	v_exp_f32_e32 v69, v69
	v_exp_f32_e32 v70, v70
	v_exp_f32_e32 v71, v71
	v_mfma_f32_32x32x16_bf16 v[18:33], v[218:221], v[90:93], v[18:33]
	ds_read_b128 v[218:221], v247 offset:24576
	v_exp_f32_e32 v72, v72
	v_exp_f32_e32 v73, v73
	v_pk_add_f32 v[252:253], v[252:253], v[66:67]
	v_pk_add_f32 v[252:253], v[252:253], v[68:69]
	v_cvt_pk_bf16_f32 v66, v66, v67
	v_mfma_f32_32x32x16_bf16 v[2:17], v[222:225], v[90:93], v[2:17]
	ds_read_b128 v[222:225], v247 offset:28672
	v_cvt_pk_bf16_f32 v67, v68, v69
	v_cvt_pk_bf16_f32 v68, v70, v71
	v_cvt_pk_bf16_f32 v69, v72, v73
	v_pk_add_f32 v[252:253], v[252:253], v[70:71]
	v_pk_add_f32 v[252:253], v[252:253], v[72:73]
	s_waitcnt lgkmcnt(4)
	v_mfma_f32_32x32x16_bf16 v[50:65], v[192:195], v[66:69], v[50:65]
	v_pk_add_f32 v[74:75], v[74:75], v[248:249] op_sel_hi:[1,0]
	v_pk_add_f32 v[76:77], v[76:77], v[248:249] op_sel_hi:[1,0]
	v_pk_add_f32 v[78:79], v[78:79], v[248:249] op_sel_hi:[1,0]
	v_pk_add_f32 v[80:81], v[80:81], v[248:249] op_sel_hi:[1,0]
	v_exp_f32_e32 v74, v74
	v_mfma_f32_32x32x16_bf16 v[34:49], v[196:199], v[66:69], v[34:49]
	v_exp_f32_e32 v75, v75
	v_exp_f32_e32 v76, v76
	v_exp_f32_e32 v77, v77
	v_exp_f32_e32 v78, v78
	v_exp_f32_e32 v79, v79
	v_mfma_f32_32x32x16_bf16 v[18:33], v[202:205], v[66:69], v[18:33]
	v_exp_f32_e32 v80, v80
	v_exp_f32_e32 v81, v81
	v_pk_add_f32 v[252:253], v[252:253], v[74:75]
	v_pk_add_f32 v[252:253], v[252:253], v[76:77]
	v_cvt_pk_bf16_f32 v74, v74, v75
	v_mfma_f32_32x32x16_bf16 v[2:17], v[206:209], v[66:69], v[2:17]
	v_cvt_pk_bf16_f32 v75, v76, v77
	v_cvt_pk_bf16_f32 v76, v78, v79
	v_cvt_pk_bf16_f32 v77, v80, v81
	v_pk_add_f32 v[252:253], v[252:253], v[78:79]
	v_pk_add_f32 v[252:253], v[252:253], v[80:81]
	s_waitcnt lgkmcnt(0)
	v_mfma_f32_32x32x16_bf16 v[50:65], v[210:213], v[74:77], v[50:65]
	v_add_f32_e32 v250, v252, v253
	v_mfma_f32_32x32x16_bf16 v[34:49], v[214:217], v[74:77], v[34:49]
	v_fma_f32 v191, v191, v0, v250
	v_mfma_f32_32x32x16_bf16 v[18:33], v[218:221], v[74:77], v[18:33]
	v_mfma_f32_32x32x16_bf16 v[2:17], v[222:225], v[74:77], v[2:17]
.La_endA:
	v_add3_u32 v120, s83, v129, v151
	v_add3_u32 v201, s83, v185, v151
	ds_read_b128 v[192:195], v120
	ds_read_b128 v[196:199], v120 offset:8192
	v_add3_u32 v120, s83, v186, v151
	ds_read_b128 v[202:205], v201
	ds_read_b128 v[206:209], v201 offset:8192
	v_add3_u32 v201, s83, v187, v151
	ds_read_b128 v[210:213], v120
	ds_read_b128 v[214:217], v120 offset:8192
	ds_read_b128 v[218:221], v201
	ds_read_b128 v[222:225], v201 offset:8192
	s_add_i32 s5, s81, 3
	s_cmp_ge_u32 s5, s73
	s_cbranch_scc1 .La_qk_nodmaB
	s_add_i32 s5, s82, 0x18000
	s_and_b32 s5, s5, 0x18000
	s_add_i32 s5, s72, s5
	s_mov_b32 m0, s5
	s_waitcnt lgkmcnt(4)
	v_mfma_f32_32x32x16_bf16 v[82:97], v[192:195], v[98:101], v[226:241]
	global_load_lds_dwordx4 v[140:141], off
	s_add_i32 m0, s5, 0x400
	v_mfma_f32_32x32x16_bf16 v[66:81], v[196:199], v[98:101], v[226:241]
	global_load_lds_dwordx4 v[138:139], off
	s_add_i32 m0, s5, 0x4000
	v_mfma_f32_32x32x16_bf16 v[82:97], v[202:205], v[102:105], v[82:97]
	global_load_lds_dwordx4 v134, s[44:45]
	s_add_i32 m0, s5, 0x4400
	v_mfma_f32_32x32x16_bf16 v[66:81], v[206:209], v[102:105], v[66:81]
	global_load_lds_dwordx4 v136, s[44:45]
	s_waitcnt lgkmcnt(0)
	v_mfma_f32_32x32x16_bf16 v[82:97], v[210:213], v[106:109], v[82:97]
	v_mfma_f32_32x32x16_bf16 v[66:81], v[214:217], v[106:109], v[66:81]
	v_mfma_f32_32x32x16_bf16 v[82:97], v[218:221], v[110:113], v[82:97]
	v_mfma_f32_32x32x16_bf16 v[66:81], v[222:225], v[110:113], v[66:81]
	s_add_u32 s44, s44, 0xffffff80
	s_addc_u32 s45, s45, -1
	v_lshl_add_u64 v[138:139], v[138:139], 0, s[38:39]
	v_lshl_add_u64 v[140:141], v[140:141], 0, s[38:39]
	s_branch .La_qk_doneB

; __device__ __forceinline__ int crow(int r, int hi) { return (r & 3) + 8 * (r >> 2) + 4 * hi; }
; __device__ __forceinline__ void unit(LAS unsigned char* lds, bf16_t* P1, const bf16_t* vaT, int b, int h, int qblk, float lam, const float* subln_w, const float* khalf) {
;     ...
;         const int kv0 = 64 * j;
;         if (j >= NT - 2) {
; #pragma unroll
;             for (int r = 0; r < 16; ++r) { const int kv = kv0 + crow(r, hi); if (kv > qrow) S0[r] = -INFINITY; if (kv + 32 > qrow) S1[r] = -INFINITY; }
;         }
.La_qk_doneB:
	v_add_u32_e32 v244, s83, v168
	v_add_u32_e32 v245, s83, v169
	v_add_u32_e32 v246, s83, v170
	v_add_u32_e32 v247, s83, v171
	ds_read_b128 v[192:195], v244 offset:16384
	ds_read_b128 v[196:199], v244 offset:20480
	ds_read_b128 v[202:205], v244 offset:24576
	ds_read_b128 v[206:209], v244 offset:28672
	ds_read_b128 v[210:213], v245 offset:16384
	ds_read_b128 v[214:217], v245 offset:20480
	ds_read_b128 v[218:221], v245 offset:24576
	ds_read_b128 v[222:225], v245 offset:28672
	s_cmp_lg_u32 s81, 0
	s_cbranch_scc1 .La_nomaskB
	v_add_u32_e32 v243, s100, v189
	v_add_u32_e32 v250, 0x60, v243
	v_add_u32_e32 v251, 64, v243
	v_cmp_le_i32_e32 vcc, v250, v125
	s_nop 6
	v_cndmask_b32_e32 v66, v184, v66, vcc
	v_cmp_lt_i32_e32 vcc, v251, v125
	s_nop 1
	v_cndmask_b32_e32 v83, v184, v83, vcc
	v_cmp_le_i32_e32 vcc, v251, v125
	v_add_u32_e32 v251, 0x61, v243
	s_nop 0
	v_cndmask_b32_e32 v82, v184, v82, vcc
	v_cmp_le_i32_e32 vcc, v251, v125
	v_add_u32_e32 v251, 0x42, v243
	s_nop 0
	v_cndmask_b32_e32 v67, v184, v67, vcc
	v_cmp_le_i32_e32 vcc, v251, v125
	v_add_u32_e32 v251, 0x62, v243
	s_nop 0
	v_cndmask_b32_e32 v84, v184, v84, vcc
	v_cmp_le_i32_e32 vcc, v251, v125
	v_add_u32_e32 v251, 0x43, v243
	s_nop 0
	v_cndmask_b32_e32 v68, v184, v68, vcc
	v_cmp_le_i32_e32 vcc, v251, v125
	v_add_u32_e32 v251, 0x63, v243
	s_nop 0
	v_cndmask_b32_e32 v85, v184, v85, vcc
	v_cmp_le_i32_e32 vcc, v251, v125
	v_add_u32_e32 v251, 0x48, v243
	s_nop 0
	v_cndmask_b32_e32 v69, v184, v69, vcc
	v_cmp_le_i32_e32 vcc, v251, v125
	v_add_u32_e32 v251, 0x68, v243
	s_nop 0
	v_cndmask_b32_e32 v86, v184, v86, vcc
	v_cmp_le_i32_e32 vcc, v251, v125
	v_add_u32_e32 v251, 0x49, v243
	s_nop 0
	v_cndmask_b32_e32 v70, v184, v70, vcc
	v_cmp_le_i32_e32 vcc, v251, v125
	v_add_u32_e32 v251, 0x69, v243
	s_nop 0
	v_cndmask_b32_e32 v87, v184, v87, vcc
	v_cmp_le_i32_e32 vcc, v251, v125
	v_add_u32_e32 v251, 0x4a, v243
	s_nop 0
	v_cndmask_b32_e32 v71, v184, v71, vcc
	v_cmp_le_i32_e32 vcc, v251, v125
	v_add_u32_e32 v251, 0x6a, v243
	s_nop 0
	v_cndmask_b32_e32 v88, v184, v88, vcc
	v_cmp_le_i32_e32 vcc, v251, v125
	v_add_u32_e32 v251, 0x4b, v243
	s_nop 0
	v_cndmask_b32_e32 v72, v184, v72, vcc
	v_cmp_le_i32_e32 vcc, v251, v125
	v_add_u32_e32 v251, 0x6b, v243
	s_nop 0
	v_cndmask_b32_e32 v89, v184, v89, vcc
	v_cmp_le_i32_e32 vcc, v251, v125
	v_add_u32_e32 v251, 0x50, v243
	s_nop 0
	v_cndmask_b32_e32 v73, v184, v73, vcc
	v_cmp_le_i32_e32 vcc, v251, v125
	v_add_u32_e32 v251, 0x70, v243
	s_nop 0
	v_cndmask_b32_e32 v90, v184, v90, vcc
	v_cmp_le_i32_e32 vcc, v251, v125
	v_add_u32_e32 v251, 0x51, v243
	s_nop 0
	v_cndmask_b32_e32 v74, v184, v74, vcc
	v_cmp_le_i32_e32 vcc, v251, v125
	v_add_u32_e32 v251, 0x71, v243
	s_nop 0
	v_cndmask_b32_e32 v91, v184, v91, vcc
	v_cmp_le_i32_e32 vcc, v251, v125
	v_add_u32_e32 v251, 0x52, v243
	s_nop 0
	v_cndmask_b32_e32 v75, v184, v75, vcc
	v_cmp_le_i32_e32 vcc, v251, v125
	v_add_u32_e32 v251, 0x72, v243
	s_nop 0
	v_cndmask_b32_e32 v92, v184, v92, vcc
	v_cmp_le_i32_e32 vcc, v251, v125
	v_add_u32_e32 v251, 0x53, v243
	s_nop 0
	v_cndmask_b32_e32 v76, v184, v76, vcc
	v_cmp_le_i32_e32 vcc, v251, v125
	v_add_u32_e32 v251, 0x73, v243
	s_nop 0
	v_cndmask_b32_e32 v93, v184, v93, vcc
	v_cmp_le_i32_e32 vcc, v251, v125
	v_add_u32_e32 v251, 0x58, v243
	s_nop 0
	v_cndmask_b32_e32 v77, v184, v77, vcc
	v_cmp_le_i32_e32 vcc, v251, v125
	v_add_u32_e32 v251, 0x78, v243
	s_nop 0
	v_cndmask_b32_e32 v94, v184, v94, vcc
	v_cmp_le_i32_e32 vcc, v251, v125
	v_add_u32_e32 v251, 0x59, v243
	s_nop 0
	v_cndmask_b32_e32 v78, v184, v78, vcc
	v_cmp_le_i32_e32 vcc, v251, v125
	v_add_u32_e32 v251, 0x79, v243
	s_nop 0
	v_cndmask_b32_e32 v95, v184, v95, vcc
	v_cmp_le_i32_e32 vcc, v251, v125
	v_add_u32_e32 v251, 0x5a, v243
	s_nop 0
	v_cndmask_b32_e32 v79, v184, v79, vcc
	v_cmp_le_i32_e32 vcc, v251, v125
	v_add_u32_e32 v251, 0x7a, v243
	s_nop 0
	v_cndmask_b32_e32 v96, v184, v96, vcc
	v_cmp_le_i32_e32 vcc, v251, v125
	v_add_u32_e32 v251, 0x5b, v243
	v_add_u32_e32 v243, 0x7b, v243
	v_cndmask_b32_e32 v80, v184, v80, vcc
	v_cmp_le_i32_e32 vcc, v251, v125
	s_nop 1
	v_cndmask_b32_e32 v97, v184, v97, vcc
	v_cmp_le_i32_e32 vcc, v243, v125
	s_nop 1
	v_cndmask_b32_e32 v81, v184, v81, vcc
; __device__ __forceinline__ float ex2(float v) { return __builtin_amdgcn_exp2f(v); }
; __device__ __forceinline__ void unit(LAS unsigned char* lds, bf16_t* P1, const bf16_t* vaT, int b, int h, int qblk, float lam, const float* subln_w, const float* khalf) {
;     ...
;         const float tb0 = sl2 * (float)(kv0 - qrow), tb1 = tb0 + sl2 * 32.f;
;         float mx0 = S0[0], mx1 = S1[0];
; #pragma unroll
;         for (int r = 1; r < 16; ++r) { mx0 = fmaxf(mx0, S0[r]); mx1 = fmaxf(mx1, S1[r]); }
;         float mt = fmaxf(mx0 + tb0, mx1 + tb1); mt = fmaxf(mt, __shfl_xor(mt, 32));
;         const bool skip = __all((mt < m - 24.f) || (mt == -INFINITY));
;         if (!skip) {
;         const float mn = fmaxf(m, mt); const float alpha = ex2(m - mn); m = mn;
;         const float c0 = tb0 - mn, c1 = tb1 - mn;
;         f32x2 ps2 = (f32x2){0.f, 0.f};
; #pragma unroll
;         for (int r = 0; r < 16; r += 2) { f32x2 a = (f32x2){S0[r], S0[r + 1]} + c0, bq = (f32x2){S1[r], S1[r + 1]} + c1;
;             a.x = ex2(a.x); a.y = ex2(a.y); bq.x = ex2(bq.x); bq.y = ex2(bq.y); S0[r] = a.x; S0[r + 1] = a.y; S1[r] = bq.x; S1[r + 1] = bq.y; ps2 = ps2 + a; ps2 = ps2 + bq; }
;         l = l * alpha + (ps2.x + ps2.y);
;         if (__any(alpha != 1.f)) {
; #pragma unroll
;             for (int d = 0; d < 4; ++d) O[d] = O[d] * alpha;
;         }
.La_nomaskB:
	v_add_u32_e32 v0, s100, v190
	v_add_u32_e32 v0, 64, v0
	v_cvt_f32_i32_e32 v142, v0
	v_add_f32_e32 v143, v133, v121
	v_max3_f32 v0, v82, v83, v84
	v_max3_f32 v120, v66, v67, v68
	v_max3_f32 v0, v0, v85, v86
	v_max3_f32 v120, v120, v69, v70
	v_max3_f32 v0, v0, v87, v88
	v_max3_f32 v120, v120, v71, v72
	v_max3_f32 v0, v0, v89, v90
	v_max3_f32 v120, v120, v73, v74
	v_max3_f32 v0, v0, v91, v92
	v_max3_f32 v120, v120, v75, v76
	v_max3_f32 v0, v0, v93, v94
	v_max3_f32 v120, v120, v77, v78
	v_max3_f32 v0, v0, v95, v96
	v_max3_f32 v120, v120, v79, v80
	v_max_f32_e32 v0, v0, v97
	v_max_f32_e32 v120, v120, v81
	v_fma_f32 v248, v127, v142, v188
	v_fmac_f32_e32 v0, v127, v142
	v_add_f32_e32 v120, v248, v120
	v_max_f32_e32 v0, v0, v120
	v_mov_b32_e32 v120, v0
	s_nop 1
	v_permlane32_swap_b32_e32 v0, v120
	v_max_f32_e32 v0, v0, v120
	v_cmp_lt_f32_e32 vcc, v0, v143
	v_cmp_eq_f32_e64 s[4:5], v0, v184
	s_or_b64 s[4:5], vcc, s[4:5]
	s_cmp_eq_u64 s[4:5], exec
	s_cbranch_scc1 .La_endB
	v_max_f32_e32 v120, v133, v0
	v_mul_f32_e32 v142, v127, v142
	v_sub_f32_e32 v0, v133, v120
	v_exp_f32_e32 v0, v0
	v_sub_f32_e32 v142, v142, v120
	v_sub_f32_e32 v248, v248, v120
	v_mov_b32_e32 v133, v120
	v_cmp_neq_f32_e32 vcc, 1.0, v0
	s_cbranch_vccz .La_norescaleB
	v_pk_mul_f32 v[64:65], v[64:65], v[0:1] op_sel_hi:[1,0]
	v_pk_mul_f32 v[62:63], v[62:63], v[0:1] op_sel_hi:[1,0]
	v_pk_mul_f32 v[60:61], v[60:61], v[0:1] op_sel_hi:[1,0]
	v_pk_mul_f32 v[58:59], v[58:59], v[0:1] op_sel_hi:[1,0]
	v_pk_mul_f32 v[56:57], v[56:57], v[0:1] op_sel_hi:[1,0]
	v_pk_mul_f32 v[54:55], v[54:55], v[0:1] op_sel_hi:[1,0]
	v_pk_mul_f32 v[52:53], v[52:53], v[0:1] op_sel_hi:[1,0]
	v_pk_mul_f32 v[50:51], v[50:51], v[0:1] op_sel_hi:[1,0]
	v_pk_mul_f32 v[48:49], v[48:49], v[0:1] op_sel_hi:[1,0]
	v_pk_mul_f32 v[46:47], v[46:47], v[0:1] op_sel_hi:[1,0]
	v_pk_mul_f32 v[44:45], v[44:45], v[0:1] op_sel_hi:[1,0]
	v_pk_mul_f32 v[42:43], v[42:43], v[0:1] op_sel_hi:[1,0]
	v_pk_mul_f32 v[40:41], v[40:41], v[0:1] op_sel_hi:[1,0]
	v_pk_mul_f32 v[38:39], v[38:39], v[0:1] op_sel_hi:[1,0]
	v_pk_mul_f32 v[36:37], v[36:37], v[0:1] op_sel_hi:[1,0]
	v_pk_mul_f32 v[34:35], v[34:35], v[0:1] op_sel_hi:[1,0]
	v_pk_mul_f32 v[32:33], v[32:33], v[0:1] op_sel_hi:[1,0]
	v_pk_mul_f32 v[30:31], v[30:31], v[0:1] op_sel_hi:[1,0]
	v_pk_mul_f32 v[28:29], v[28:29], v[0:1] op_sel_hi:[1,0]
	v_pk_mul_f32 v[26:27], v[26:27], v[0:1] op_sel_hi:[1,0]
	v_pk_mul_f32 v[24:25], v[24:25], v[0:1] op_sel_hi:[1,0]
	v_pk_mul_f32 v[22:23], v[22:23], v[0:1] op_sel_hi:[1,0]
	v_pk_mul_f32 v[20:21], v[20:21], v[0:1] op_sel_hi:[1,0]
	v_pk_mul_f32 v[18:19], v[18:19], v[0:1] op_sel_hi:[1,0]
	v_pk_mul_f32 v[16:17], v[16:17], v[0:1] op_sel_hi:[1,0]
	v_pk_mul_f32 v[14:15], v[14:15], v[0:1] op_sel_hi:[1,0]
	v_pk_mul_f32 v[12:13], v[12:13], v[0:1] op_sel_hi:[1,0]
	v_pk_mul_f32 v[10:11], v[10:11], v[0:1] op_sel_hi:[1,0]
	v_pk_mul_f32 v[8:9], v[8:9], v[0:1] op_sel_hi:[1,0]
	v_pk_mul_f32 v[6:7], v[6:7], v[0:1] op_sel_hi:[1,0]
	v_pk_mul_f32 v[4:5], v[4:5], v[0:1] op_sel_hi:[1,0]
	v_pk_mul_f32 v[2:3], v[2:3], v[0:1] op_sel_hi:[1,0]

; __device__ __forceinline__ void unit(LAS unsigned char* lds, bf16_t* P1, const bf16_t* vaT, int b, int h, int qblk, float lam, const float* subln_w, const float* khalf) {
;     ...
;     int stg = 0;
; #pragma unroll 1
;     for (int jj = 0; jj < NT; ++jj) {
;         const int j = NT - 1 - jj;
.La_endB:
	s_add_i32 s80, s80, 2
	s_and_b32 s80, s80, 3
	s_add_i32 s4, s59, s76
	s_add_i32 s81, s81, 2
	s_sub_i32 s76, s76, 0x80
	s_cmp_eq_u32 s4, 0
	s_cbranch_scc0 .La_top
